# LDS exchange regions skewed by 16 B per query class (removes 8-way ds_write bank conflicts)
# speedup vs baseline: 1.0228x; 1.0065x over previous
; DI void attn_a_y(unsigned char* ws, LAS unsigned char* buf, int bh, int t0, int lane) {
;     ...
;     const float la = a.st.l + __shfl_xor(a.st.l, 32), lb = b.st.l + __shfl_xor(b.st.l, 32);
;     float* exa = (float*)(ws + WS_EXO) + ((size_t)bh * SEQ + qpa) * 64 + 4 * h;
;     float* exb = exa + 32 * 64;
; #pragma unroll
;     for (int g = 0; g < 4; ++g) {
;         *(f32x4*)(exa + 8 * g) = (f32x4){a.st.o0[4 * g], a.st.o0[4 * g + 1], a.st.o0[4 * g + 2], a.st.o0[4 * g + 3]};
;         *(f32x4*)(exa + 32 + 8 * g) = (f32x4){a.st.o1[4 * g], a.st.o1[4 * g + 1], a.st.o1[4 * g + 2], a.st.o1[4 * g + 3]};
;         *(f32x4*)(exb + 8 * g) = (f32x4){b.st.o0[4 * g], b.st.o0[4 * g + 1], b.st.o0[4 * g + 2], b.st.o0[4 * g + 3]};
;         *(f32x4*)(exb + 32 + 8 * g) = (f32x4){b.st.o1[4 * g], b.st.o1[4 * g + 1], b.st.o1[4 * g + 2], b.st.o1[4 * g + 3]};
;     }
;     if (h == 0) { float* exl = (float*)(ws + WS_EXL) + (size_t)bh * SEQ; exl[qpa] = la; exl[qpb] = lb; }
; DI void attn_a_x(unsigned char* ws, LAS unsigned char* buf, int bh, int ra, int i0, int lane) {
;     ...
;     {
;         const float* exa = (const float*)(ws + WS_EXO) + ((size_t)bh * SEQ + qpa) * 64 + 4 * h;
;         const float* exb = exa + 8 * 64;
; #pragma unroll
;         for (int g = 0; g < 4; ++g) {
;             const f32x4 a0 = *(const f32x4*)(exa + 8 * g), a1 = *(const f32x4*)(exa + 32 + 8 * g), b0 = *(const f32x4*)(exb + 8 * g), b1 = *(const f32x4*)(exb + 32 + 8 * g);
; #pragma unroll
;             for (int j = 0; j < 4; ++j) { a.st.o0[4 * g + j] = a0[j]; a.st.o1[4 * g + j] = a1[j]; b.st.o0[4 * g + j] = b0[j]; b.st.o1[4 * g + j] = b1[j]; }
;         }
;         const float* exl = (const float*)(ws + WS_EXL) + (size_t)bh * SEQ;
;         a.st.l = (h == 0) ? exl[qpa] : 0.f; b.st.l = (h == 0) ? exl[qpb] : 0.f;
;     }
.LBB0_601:
	ds_bpermute_b32 v64, v191, v189
	ds_bpermute_b32 v65, v191, v188
	v_and_b32_e32 v66, 7, v234
	v_lshlrev_b32_e32 v66, 5, v66
	v_lshrrev_b32_e32 v67, 6, v234
	v_lshl_add_u32 v66, v67, 2, v66
	v_bfe_u32 v80, v234, 4, 1
	v_add_u32_e32 v66, v66, v80
	v_mul_u32_u24_e32 v66, 0x110, v66
	v_bfe_u32 v80, v234, 5, 1
	v_lshlrev_b32_e32 v80, 4, v80
	v_add_u32_e32 v66, v66, v80
	v_add_u32_e32 v66, 0x12000, v66
	v_lshlrev_b32_e32 v67, 5, v67
	v_and_b32_e32 v68, 31, v234
	v_add_u32_e32 v67, v67, v68
	v_mul_u32_u24_e32 v67, 0x110, v67
	v_add_u32_e32 v67, v67, v80
	v_add_u32_e32 v67, 0x12000, v67
	v_and_b32_e32 v68, 7, v234
	v_lshl_add_u32 v66, v68, 4, v66
	v_lshrrev_b32_e32 v68, 6, v234
	v_lshl_add_u32 v67, v68, 4, v67
	s_waitcnt lgkmcnt(0)
	v_add_f32_e32 v64, v189, v64
	v_add_f32_e32 v65, v188, v65
	s_mov_b32 exec_lo, 0xff00ff
	s_mov_b32 exec_hi, 0xff00ff
	ds_write_b128 v66, v[32:35] offset:0
	ds_write_b128 v66, v[36:39] offset:32
	ds_write_b128 v66, v[40:43] offset:64
	ds_write_b128 v66, v[44:47] offset:96
	ds_write_b128 v66, v[48:51] offset:128
	ds_write_b128 v66, v[52:55] offset:160
	ds_write_b128 v66, v[56:59] offset:192
	ds_write_b128 v66, v[60:63] offset:224
	ds_write_b128 v66, v[16:19] offset:544
	ds_write_b128 v66, v[20:23] offset:576
	ds_write_b128 v66, v[24:27] offset:608
	ds_write_b128 v66, v[28:31] offset:640
	ds_write_b128 v66, v[0:3] offset:672
	ds_write_b128 v66, v[4:7] offset:704
	ds_write_b128 v66, v[8:11] offset:736
	ds_write_b128 v66, v[12:15] offset:768
	s_mov_b32 exec_hi, 0
	ds_write_b32 v66, v64 offset:256
	ds_write_b32 v66, v65 offset:800
	s_mov_b64 exec, -1
	s_waitcnt lgkmcnt(0)
	s_barrier
	ds_read_b128 v[144:147], v67 offset:0
	ds_read_b128 v[148:151], v67 offset:32
	ds_read_b128 v[152:155], v67 offset:64
	ds_read_b128 v[156:159], v67 offset:96
	ds_read_b128 v[160:163], v67 offset:128
	ds_read_b128 v[164:167], v67 offset:160
	ds_read_b128 v[168:171], v67 offset:192
	ds_read_b128 v[172:175], v67 offset:224
	v_mov_b32_e32 v68, 0
	s_mov_b32 exec_hi, 0
	ds_read_b32 v68, v67 offset:256
	s_mov_b64 exec, -1
	s_waitcnt lgkmcnt(0)
	s_barrier
	s_mov_b32 exec_lo, 0xff00ff00
	s_mov_b32 exec_hi, 0xff00ff00
	ds_write_b128 v66, v[32:35] offset:0
	ds_write_b128 v66, v[36:39] offset:32
	ds_write_b128 v66, v[40:43] offset:64
	ds_write_b128 v66, v[44:47] offset:96
	ds_write_b128 v66, v[48:51] offset:128
	ds_write_b128 v66, v[52:55] offset:160
	ds_write_b128 v66, v[56:59] offset:192
	ds_write_b128 v66, v[60:63] offset:224
	ds_write_b128 v66, v[16:19] offset:544
	ds_write_b128 v66, v[20:23] offset:576
	ds_write_b128 v66, v[24:27] offset:608
	ds_write_b128 v66, v[28:31] offset:640
	ds_write_b128 v66, v[0:3] offset:672
	ds_write_b128 v66, v[4:7] offset:704
	ds_write_b128 v66, v[8:11] offset:736
	ds_write_b128 v66, v[12:15] offset:768
	s_mov_b32 exec_hi, 0
	ds_write_b32 v66, v64 offset:256
	ds_write_b32 v66, v65 offset:800
	s_mov_b64 exec, -1
	s_waitcnt lgkmcnt(0)
	s_barrier
